# GEMM phase prologue: K-tile 1 staging loads issued before the first wait (one exposed round trip fewer per GEMM phase entry)
# speedup vs baseline: 1.0003x; 1.0003x over previous
.LBB0_342:
	v_and_b32_e32 v7, 15, v6
	v_readlane_b32 s0, v251, 46
	v_lshrrev_b32_e32 v16, 1, v6
	v_and_b32_e32 v16, 24, v16
	v_or_b32_e32 v153, s0, v7
	v_lshlrev_b32_e32 v17, 6, v153
	v_lshlrev_b32_e32 v18, 1, v16
	s_movk_i32 s0, 0x3c0
	v_lshlrev_b32_e32 v19, 2, v153
	v_and_or_b32 v17, v17, s0, v18
	v_and_b32_e32 v19, 32, v19
	v_readlane_b32 s0, v251, 47
	v_lshlrev_b32_e32 v6, 2, v6
	v_mov_b32_e32 v143, v97
	v_bitop3_b32 v17, v17, s0, v19 bitop3:0xde
	v_lshl_or_b32 v7, v7, 6, v18
	v_and_b32_e32 v6, 32, v6
	v_readlane_b32 s0, v251, 49
	v_lshl_add_u64 v[8:9], s[44:45], 0, v[142:143]
	v_mov_b32_e32 v139, v97
	v_bitop3_b32 v158, v7, s0, v6 bitop3:0xde
	s_add_u32 s0, s58, 0x25400000
	v_lshl_add_u64 v[10:11], s[44:45], 0, v[138:139]
	v_mov_b32_e32 v145, v97
	s_addc_u32 s1, s59, 0
	v_lshl_add_u64 v[6:7], v[8:9], 0, s[64:65]
	s_add_i32 m0, s35, 0x18000
	v_lshl_add_u64 v[12:13], s[42:43], 0, v[144:145]
	v_mov_b32_e32 v141, v97
	v_mov_b32_e32 v243, 0
	global_load_lds_dwordx4 v[6:7], off
	v_lshl_add_u64 v[6:7], v[10:11], 0, s[64:65]
	s_add_i32 m0, s35, 0x1a000
	s_add_i32 s79, s35, 0x8000
	s_add_i32 s81, s35, 0xa000
	v_lshl_add_u64 v[14:15], s[42:43], 0, v[140:141]
	global_load_lds_dwordx4 v[6:7], off
	v_lshl_add_u64 v[6:7], v[12:13], 0, s[64:65]
	s_mov_b32 m0, s79
	s_add_u32 s2, s44, 0x80080
	global_load_lds_dwordx4 v[6:7], off
	v_lshl_add_u64 v[6:7], v[14:15], 0, s[64:65]
	s_mov_b32 m0, s81
	s_addc_u32 s3, s45, 0
	global_load_lds_dwordx4 v[6:7], off
	v_lshl_add_u64 v[6:7], s[2:3], 0, v[142:143]
	s_add_i32 m0, s35, 0x1c000
	v_readlane_b32 s4, v250, 11
	global_load_lds_dwordx4 v[6:7], off
	v_lshl_add_u64 v[6:7], s[2:3], 0, v[138:139]
	s_add_i32 m0, s35, 0x1e000
	v_readlane_b32 s2, v251, 48
	global_load_lds_dwordx4 v[6:7], off
	s_waitcnt vmcnt(8)
	s_barrier
	v_lshlrev_b32_e32 v7, 15, v3
	v_and_b32_e32 v7, 0xffff0000, v7
	v_lshl_add_u32 v4, v4, 12, v7
	v_and_b32_e32 v3, 1, v3
	v_lshl_or_b32 v3, v3, 6, v4
	v_lshl_add_u32 v146, v5, 1, v3
	v_lshlrev_b32_e32 v3, 15, v0
	v_and_b32_e32 v3, 0xffff0000, v3
	s_waitcnt vmcnt(6)
	v_lshl_add_u32 v1, v1, 12, v3
	v_and_b32_e32 v0, 1, v0
	v_or_b32_e32 v6, s2, v16
	v_lshl_or_b32 v0, v0, 6, v1
	v_mov_b32_e32 v147, v97
	v_lshl_add_u32 v148, v2, 1, v0
	v_mov_b32_e32 v149, v97
	s_mov_b32 s2, 0
	v_add_u32_e32 v159, 0, v17
	v_lshlrev_b32_e32 v96, 1, v6
	v_readlane_b32 s12, v252, 54
	s_mov_b32 s3, s4
	s_movk_i32 s13, 0x1800
	s_barrier
	v_readlane_b32 s5, v250, 12
	s_branch .LBB0_345

.LBB0_630:
	s_add_u32 s24, s4, 0x2ff00000
	s_addc_u32 s25, s5, 0
	v_lshl_add_u64 v[0:1], v[0:1], 0, s[64:65]
	s_add_i32 m0, s10, 0x18000
	v_mov_b32_e32 v243, 0
	global_load_lds_dwordx4 v[0:1], off
	v_lshl_add_u64 v[0:1], v[2:3], 0, s[64:65]
	s_add_i32 m0, s10, 0x1a000
	s_add_i32 s26, s10, 0x8000
	s_add_i32 s27, s10, 0xa000
	global_load_lds_dwordx4 v[0:1], off
	v_lshl_add_u64 v[0:1], v[4:5], 0, s[64:65]
	s_mov_b32 m0, s26
	s_add_u32 s30, s82, 0x20080
	global_load_lds_dwordx4 v[0:1], off
	v_lshl_add_u64 v[0:1], v[6:7], 0, s[64:65]
	s_mov_b32 m0, s27
	s_addc_u32 s31, s83, 0
	global_load_lds_dwordx4 v[0:1], off
	v_lshl_add_u64 v[0:1], s[30:31], 0, v[96:97]
	s_add_i32 m0, s10, 0x1c000
	v_and_b32_e32 v15, 15, v14
	global_load_lds_dwordx4 v[0:1], off
	v_lshl_add_u64 v[0:1], s[30:31], 0, v[130:131]
	s_add_i32 m0, s10, 0x1e000
	v_readlane_b32 s6, v251, 46
	global_load_lds_dwordx4 v[0:1], off
	s_waitcnt vmcnt(8)
	s_barrier
	v_lshlrev_b32_e32 v0, 13, v11
	v_lshrrev_b32_e32 v16, 1, v14
	v_and_b32_e32 v0, 0xffffc000, v0
	v_or_b32_e32 v141, s6, v15
	v_and_b32_e32 v16, 24, v16
	v_lshl_add_u32 v0, v12, 10, v0
	v_and_b32_e32 v1, 1, v11
	v_lshlrev_b32_e32 v17, 6, v141
	v_lshlrev_b32_e32 v18, 1, v16
	s_movk_i32 s6, 0x3c0
	v_lshlrev_b32_e32 v19, 2, v141
	v_lshl_or_b32 v0, v1, 6, v0
	v_and_or_b32 v17, v17, s6, v18
	v_and_b32_e32 v19, 32, v19
	v_readlane_b32 s6, v251, 47
	v_lshlrev_b32_e32 v14, 2, v14
	v_lshl_add_u32 v136, v13, 1, v0
	v_lshlrev_b32_e32 v0, 13, v8
	v_bitop3_b32 v17, v17, s6, v19 bitop3:0xde
	v_lshl_or_b32 v15, v15, 6, v18
	v_and_b32_e32 v14, 32, v14
	v_readlane_b32 s6, v251, 49
	v_and_b32_e32 v0, 0xffffc000, v0
	s_waitcnt vmcnt(6)
	v_lshl_add_u32 v0, v9, 10, v0
	v_bitop3_b32 v142, v15, s6, v14 bitop3:0xde
	v_readlane_b32 s6, v251, 48
	v_and_b32_e32 v1, 1, v8
	v_lshl_or_b32 v0, v1, 6, v0
	v_or_b32_e32 v143, s6, v16
	v_readlane_b32 s6, v252, 63
	v_mov_b32_e32 v137, v97
	v_lshl_add_u32 v138, v10, 1, v0
	v_mov_b32_e32 v139, v97
	s_mov_b32 s28, 0
	v_add_u32_e32 v144, 0, v17
	v_readlane_b32 s33, v252, 41
	s_mov_b32 s34, s6
	s_barrier
	v_readlane_b32 s7, v250, 0
	s_branch .LBB0_633

.LBB0_646:
	s_add_u32 s24, s4, 0x33000000
	s_addc_u32 s25, s5, 0
	v_lshl_add_u64 v[0:1], v[0:1], 0, s[64:65]
	s_add_i32 m0, s18, 0x18000
	v_mov_b32_e32 v243, 0
	global_load_lds_dwordx4 v[0:1], off
	v_lshl_add_u64 v[0:1], v[2:3], 0, s[64:65]
	s_add_i32 m0, s18, 0x1a000
	s_add_i32 s28, s18, 0x8000
	s_add_i32 s33, s18, 0xa000
	global_load_lds_dwordx4 v[0:1], off
	v_lshl_add_u64 v[0:1], v[4:5], 0, s[64:65]
	s_mov_b32 m0, s28
	s_add_u32 s30, s82, 0x20080
	global_load_lds_dwordx4 v[0:1], off
	v_lshl_add_u64 v[0:1], v[6:7], 0, s[64:65]
	s_mov_b32 m0, s33
	s_addc_u32 s31, s83, 0
	global_load_lds_dwordx4 v[0:1], off
	v_lshl_add_u64 v[0:1], s[30:31], 0, v[96:97]
	s_add_i32 m0, s18, 0x1c000
	v_and_b32_e32 v15, 15, v14
	global_load_lds_dwordx4 v[0:1], off
	v_lshl_add_u64 v[0:1], s[30:31], 0, v[130:131]
	s_add_i32 m0, s18, 0x1e000
	v_readlane_b32 s6, v251, 46
	global_load_lds_dwordx4 v[0:1], off
	s_waitcnt vmcnt(8)
	s_barrier
	v_lshlrev_b32_e32 v0, 13, v11
	v_lshrrev_b32_e32 v16, 1, v14
	v_and_b32_e32 v0, 0xffffc000, v0
	v_or_b32_e32 v141, s6, v15
	v_and_b32_e32 v16, 24, v16
	v_lshl_add_u32 v0, v12, 10, v0
	v_and_b32_e32 v1, 1, v11
	v_lshlrev_b32_e32 v17, 6, v141
	v_lshlrev_b32_e32 v18, 1, v16
	s_movk_i32 s6, 0x3c0
	v_lshlrev_b32_e32 v19, 2, v141
	v_lshl_or_b32 v0, v1, 6, v0
	v_and_or_b32 v17, v17, s6, v18
	v_and_b32_e32 v19, 32, v19
	v_readlane_b32 s6, v251, 47
	v_lshlrev_b32_e32 v14, 2, v14
	v_lshl_add_u32 v136, v13, 1, v0
	v_lshlrev_b32_e32 v0, 13, v8
	v_bitop3_b32 v17, v17, s6, v19 bitop3:0xde
	v_lshl_or_b32 v15, v15, 6, v18
	v_and_b32_e32 v14, 32, v14
	v_readlane_b32 s6, v251, 49
	v_and_b32_e32 v0, 0xffffc000, v0
	s_waitcnt vmcnt(6)
	v_lshl_add_u32 v0, v9, 10, v0
	v_bitop3_b32 v142, v15, s6, v14 bitop3:0xde
	v_readlane_b32 s6, v251, 48
	v_and_b32_e32 v1, 1, v8
	v_lshl_or_b32 v0, v1, 6, v0
	v_or_b32_e32 v143, s6, v16
	v_readlane_b32 s6, v250, 15
	v_mov_b32_e32 v137, v97
	v_lshl_add_u32 v138, v10, 1, v0
	v_mov_b32_e32 v139, v97
	s_mov_b32 s34, 0
	v_add_u32_e32 v144, 0, v17
	v_readlane_b32 s35, v252, 44
	s_mov_b32 s50, s6
	s_barrier
	v_readlane_b32 s7, v250, 16
	s_branch .LBB0_649

.LBB0_1028:
	v_readlane_b32 s0, v254, 12
	s_mul_i32 s3, s0, 0x120000
	s_mul_hi_u32 s2, s0, 0x120000
	s_add_u32 s16, s26, s3
	v_readlane_b32 s1, v254, 13
	s_addc_u32 s17, s27, s2
	s_cmp_eq_u32 s0, 0
	v_readlane_b32 s0, v249, 12
	v_readlane_b32 s1, v249, 13
	v_readlane_b32 s4, v249, 16
	v_readlane_b32 s5, v249, 17
	s_cselect_b32 s5, s1, 0
	s_cselect_b32 s4, s0, 0
	s_add_u32 s92, s16, 0x204000
	s_addc_u32 s93, s17, 0
	s_add_u32 s16, s26, 0x19000000
	s_addc_u32 s17, s27, 0
	v_lshl_add_u64 v[0:1], v[0:1], 0, s[64:65]
	s_add_i32 m0, s58, 0x18000
	v_readlane_b32 s2, v249, 14
	v_mov_b32_e32 v243, 0
	global_load_lds_dwordx4 v[0:1], off
	v_lshl_add_u64 v[0:1], v[2:3], 0, s[64:65]
	s_add_i32 m0, s58, 0x1a000
	s_add_i32 s94, s58, 0x8000
	s_add_i32 s95, s58, 0xa000
	v_readlane_b32 s3, v249, 15
	global_load_lds_dwordx4 v[0:1], off
	v_lshl_add_u64 v[0:1], v[4:5], 0, s[64:65]
	s_mov_b32 m0, s94
	s_add_u32 s2, s84, 0x80080
	global_load_lds_dwordx4 v[0:1], off
	v_lshl_add_u64 v[0:1], v[6:7], 0, s[64:65]
	s_mov_b32 m0, s95
	s_addc_u32 s3, s85, 0
	global_load_lds_dwordx4 v[0:1], off
	v_lshl_add_u64 v[0:1], s[2:3], 0, v[96:97]
	s_add_i32 m0, s58, 0x1c000
	v_and_b32_e32 v15, 15, v14
	global_load_lds_dwordx4 v[0:1], off
	v_lshl_add_u64 v[0:1], s[2:3], 0, v[142:143]
	s_add_i32 m0, s58, 0x1e000
	v_readlane_b32 s0, v251, 46
	global_load_lds_dwordx4 v[0:1], off
	s_waitcnt vmcnt(8)
	s_barrier
	v_lshlrev_b32_e32 v0, 15, v11
	v_lshrrev_b32_e32 v16, 1, v14
	v_and_b32_e32 v0, 0xffff0000, v0
	v_or_b32_e32 v168, s0, v15
	v_and_b32_e32 v16, 24, v16
	v_lshl_add_u32 v0, v12, 12, v0
	v_and_b32_e32 v1, 1, v11
	v_lshlrev_b32_e32 v17, 6, v168
	v_lshlrev_b32_e32 v18, 1, v16
	s_movk_i32 s0, 0x3c0
	v_lshlrev_b32_e32 v19, 2, v168
	v_lshl_or_b32 v0, v1, 6, v0
	v_and_or_b32 v17, v17, s0, v18
	v_and_b32_e32 v19, 32, v19
	v_readlane_b32 s0, v251, 47
	v_lshlrev_b32_e32 v14, 2, v14
	v_lshl_add_u32 v148, v13, 1, v0
	v_lshlrev_b32_e32 v0, 15, v8
	v_bitop3_b32 v17, v17, s0, v19 bitop3:0xde
	v_lshl_or_b32 v15, v15, 6, v18
	v_and_b32_e32 v14, 32, v14
	v_readlane_b32 s0, v251, 49
	v_and_b32_e32 v0, 0xffff0000, v0
	s_waitcnt vmcnt(6)
	v_lshl_add_u32 v0, v9, 12, v0
	v_bitop3_b32 v169, v15, s0, v14 bitop3:0xde
	v_readlane_b32 s0, v251, 48
	v_and_b32_e32 v1, 1, v8
	s_cmp_lg_u64 s[4:5], 0
	v_or_b32_e32 v170, s0, v16
	v_lshl_or_b32 v0, v1, 6, v0
	v_readlane_b32 s0, v250, 15
	v_readlane_b32 s54, v253, 60
	s_mov_b32 s91, 0
	s_cselect_b64 s[24:25], -1, 0
	v_mov_b32_e32 v149, v97
	v_lshl_add_u32 v150, v10, 1, v0
	v_mov_b32_e32 v151, v97
	v_add_u32_e32 v171, 0, v17
	v_readlane_b32 s3, v252, 44
	s_mov_b32 s2, s0
	v_readlane_b32 s55, v253, 61
	v_readlane_b32 s6, v249, 18
	v_readlane_b32 s7, v249, 19
	v_readlane_b32 s8, v249, 20
	v_readlane_b32 s9, v249, 21
	v_readlane_b32 s10, v249, 22
	v_readlane_b32 s11, v249, 23
	v_readlane_b32 s12, v249, 24
	v_readlane_b32 s13, v249, 25
	v_readlane_b32 s14, v249, 26
	v_readlane_b32 s15, v249, 27
	s_barrier
	v_readlane_b32 s1, v250, 16
	s_branch .LBB0_1031

.LBB0_1255:
	v_readlane_b32 s0, v254, 12
	v_readlane_b32 s1, v254, 13
	s_mov_b32 s2, s0
	s_mul_i32 s1, s2, 0x120000
	s_mul_hi_u32 s0, s0, 0x120000
	s_add_u32 s1, s14, s1
	s_addc_u32 s0, s26, s0
	s_add_u32 s84, s1, 0x20a000
	s_addc_u32 s85, s0, 0
	v_and_b32_e32 v15, 15, v14
	v_readlane_b32 s0, v251, 46
	v_lshrrev_b32_e32 v16, 1, v14
	v_and_b32_e32 v16, 24, v16
	v_or_b32_e32 v152, s0, v15
	v_lshlrev_b32_e32 v17, 6, v152
	v_lshlrev_b32_e32 v18, 1, v16
	s_movk_i32 s0, 0x3c0
	v_lshlrev_b32_e32 v19, 2, v152
	v_and_or_b32 v17, v17, s0, v18
	v_and_b32_e32 v19, 32, v19
	v_readlane_b32 s0, v251, 47
	v_lshlrev_b32_e32 v14, 2, v14
	v_lshl_or_b32 v15, v15, 6, v18
	v_bitop3_b32 v17, v17, s0, v19 bitop3:0xde
	v_and_b32_e32 v14, 32, v14
	v_readlane_b32 s0, v251, 49
	v_lshl_add_u64 v[0:1], v[0:1], 0, s[64:65]
	v_mov_b32_e32 v243, 0
	v_bitop3_b32 v153, v15, s0, v14 bitop3:0xde
	s_add_u32 s0, s14, 0x19000000
	s_addc_u32 s1, s26, 0
	s_add_i32 m0, s59, 0x18000
	s_add_i32 s10, s59, 0x8000
	global_load_lds_dwordx4 v[0:1], off
	v_lshl_add_u64 v[0:1], v[2:3], 0, s[64:65]
	s_add_i32 m0, s59, 0x1a000
	s_add_i32 s77, s59, 0xa000
	global_load_lds_dwordx4 v[0:1], off
	v_lshl_add_u64 v[0:1], v[4:5], 0, s[64:65]
	s_mov_b32 m0, s10
	s_add_u32 s2, s44, 0x200080
	global_load_lds_dwordx4 v[0:1], off
	v_lshl_add_u64 v[0:1], v[6:7], 0, s[64:65]
	s_mov_b32 m0, s77
	s_addc_u32 s3, s45, 0
	global_load_lds_dwordx4 v[0:1], off
	v_lshl_add_u64 v[0:1], s[2:3], 0, v[96:97]
	s_add_i32 m0, s59, 0x1c000
	v_readlane_b32 s4, v250, 15
	global_load_lds_dwordx4 v[0:1], off
	v_lshl_add_u64 v[0:1], s[2:3], 0, v[134:135]
	s_add_i32 m0, s59, 0x1e000
	v_readlane_b32 s2, v251, 48
	global_load_lds_dwordx4 v[0:1], off
	s_waitcnt vmcnt(8)
	s_barrier
	v_lshlrev_b32_e32 v0, 17, v11
	v_and_b32_e32 v0, 0xfffc0000, v0
	v_lshl_add_u32 v0, v12, 14, v0
	v_and_b32_e32 v1, 1, v11
	v_lshl_or_b32 v0, v1, 6, v0
	v_lshl_add_u32 v140, v13, 1, v0
	v_lshlrev_b32_e32 v0, 17, v8
	v_and_b32_e32 v0, 0xfffc0000, v0
	s_waitcnt vmcnt(6)
	v_lshl_add_u32 v0, v9, 14, v0
	v_and_b32_e32 v1, 1, v8
	v_lshl_or_b32 v0, v1, 6, v0
	v_or_b32_e32 v158, s2, v16
	v_mov_b32_e32 v141, v97
	v_lshl_add_u32 v142, v10, 1, v0
	v_mov_b32_e32 v143, v97
	s_mov_b32 s34, 0
	v_add_u32_e32 v159, 0, v17
	v_readlane_b32 s3, v252, 44
	s_mov_b32 s2, s4
	s_barrier
	v_readlane_b32 s5, v250, 16
	s_branch .LBB0_1258

.LBB0_1274:
	v_and_b32_e32 v7, 15, v6
	v_readlane_b32 s0, v251, 46
	v_lshrrev_b32_e32 v16, 1, v6
	v_and_b32_e32 v16, 24, v16
	v_or_b32_e32 v133, s0, v7
	v_lshlrev_b32_e32 v17, 6, v133
	v_lshlrev_b32_e32 v18, 1, v16
	s_movk_i32 s0, 0x3c0
	v_lshlrev_b32_e32 v19, 2, v133
	v_and_or_b32 v17, v17, s0, v18
	v_and_b32_e32 v19, 32, v19
	v_readlane_b32 s0, v251, 47
	v_lshlrev_b32_e32 v6, 2, v6
	v_lshl_or_b32 v7, v7, 6, v18
	v_bitop3_b32 v17, v17, s0, v19 bitop3:0xde
	v_and_b32_e32 v6, 32, v6
	v_readlane_b32 s0, v251, 49
	v_lshl_add_u64 v[8:9], s[68:69], 0, v[96:97]
	v_mov_b32_e32 v135, v97
	v_bitop3_b32 v150, v7, s0, v6 bitop3:0xde
	v_readlane_b32 s0, v254, 30
	v_readlane_b32 s1, v254, 31
	s_add_u32 s4, s0, 0x25400000
	v_lshl_add_u64 v[10:11], s[68:69], 0, v[134:135]
	v_mov_b32_e32 v139, v97
	s_addc_u32 s5, s1, 0
	v_lshl_add_u64 v[6:7], v[8:9], 0, s[64:65]
	s_add_i32 m0, s34, 0x18000
	v_lshl_add_u64 v[12:13], s[52:53], 0, v[138:139]
	v_mov_b32_e32 v137, v97
	v_mov_b32_e32 v243, 0
	global_load_lds_dwordx4 v[6:7], off
	v_lshl_add_u64 v[6:7], v[10:11], 0, s[64:65]
	s_add_i32 m0, s34, 0x1a000
	s_add_i32 s58, s34, 0x8000
	s_add_i32 s59, s34, 0xa000
	v_lshl_add_u64 v[14:15], s[52:53], 0, v[136:137]
	global_load_lds_dwordx4 v[6:7], off
	v_lshl_add_u64 v[6:7], v[12:13], 0, s[64:65]
	s_mov_b32 m0, s58
	s_add_u32 s0, s68, 0x80080
	global_load_lds_dwordx4 v[6:7], off
	v_lshl_add_u64 v[6:7], v[14:15], 0, s[64:65]
	s_mov_b32 m0, s59
	s_addc_u32 s1, s69, 0
	global_load_lds_dwordx4 v[6:7], off
	v_lshl_add_u64 v[6:7], s[0:1], 0, v[96:97]
	s_add_i32 m0, s34, 0x1c000
	v_mov_b32_e32 v141, v97
	global_load_lds_dwordx4 v[6:7], off
	v_lshl_add_u64 v[6:7], s[0:1], 0, v[134:135]
	s_add_i32 m0, s34, 0x1e000
	v_readlane_b32 s0, v251, 48
	global_load_lds_dwordx4 v[6:7], off
	s_waitcnt vmcnt(8)
	s_barrier
	v_lshlrev_b32_e32 v6, 15, v3
	v_and_b32_e32 v6, 0xffff0000, v6
	v_lshl_add_u32 v4, v4, 12, v6
	v_and_b32_e32 v3, 1, v3
	v_lshl_or_b32 v3, v3, 6, v4
	v_lshl_add_u32 v140, v5, 1, v3
	v_lshlrev_b32_e32 v3, 15, v0
	v_and_b32_e32 v3, 0xffff0000, v3
	s_waitcnt vmcnt(6)
	v_lshl_add_u32 v1, v1, 12, v3
	v_and_b32_e32 v0, 1, v0
	v_lshl_or_b32 v0, v0, 6, v1
	v_or_b32_e32 v151, s0, v16
	v_lshl_add_u32 v142, v2, 1, v0
	v_mov_b32_e32 v143, v97
	s_mov_b32 s0, 0
	v_add_u32_e32 v152, 0, v17
	v_readlane_b32 s1, v252, 51
	v_readlane_b32 s2, v250, 5
	s_barrier
	v_readlane_b32 s3, v250, 6
	s_branch .LBB0_1277
